# grid barrier release flattened: all workgroups poll the cross-XCD arrival counter directly (no TOPGEN/XGEN hops), on v17
# speedup vs baseline: 1.0160x; 1.0057x over previous
.LBB0_329:
	v_readlane_b32 s3, v254, 41
	s_add_u32 s26, s4, s3
	s_addc_u32 s3, s5, 0
	v_mov_b32_e32 v1, s26
	v_add_co_u32_e32 v6, vcc, 0x1000, v1
	v_mov_b32_e32 v1, s3
	s_nop 0
	v_addc_co_u32_e32 v7, vcc, 0, v1, vcc
	flat_atomic_add v1, v[6:7], v223 offset:1024 sc0
	v_cvt_f32_u32_e32 v3, v4
	v_sub_u32_e32 v5, 0, v4
	v_rcp_iflag_f32_e32 v3, v3
	s_nop 0
	v_mul_f32_e32 v3, 0x4f7ffffe, v3
	v_cvt_u32_f32_e32 v3, v3
	v_mul_lo_u32 v5, v5, v3
	v_mul_hi_u32 v5, v3, v5
	v_add_u32_e32 v3, v3, v5
	s_waitcnt vmcnt(0) lgkmcnt(0)
	v_mul_hi_u32 v3, v1, v3
	v_mul_lo_u32 v5, v3, v4
	v_add_u32_e32 v6, 1, v1
	v_sub_u32_e32 v1, v1, v5
	v_add_u32_e32 v7, 1, v3
	v_cmp_ge_u32_e32 vcc, v1, v4
	v_sub_u32_e32 v5, v1, v4
	s_nop 0
	v_cndmask_b32_e32 v3, v3, v7, vcc
	v_cndmask_b32_e32 v1, v1, v5, vcc
	v_add_u32_e32 v5, 1, v3
	v_cmp_ge_u32_e32 vcc, v1, v4
	s_nop 1
	v_cndmask_b32_e32 v1, v3, v5, vcc
	v_mad_u64_u32 v[4:5], s[6:7], v4, v1, v[4:5]
	v_cmp_ne_u32_e32 vcc, v6, v4
	s_and_saveexec_b64 s[6:7], vcc
	s_xor_b64 s[6:7], exec, s[6:7]
	s_cbranch_execz .LBB0_342
	v_add_u32_e32 v8, 1, v1
	v_mul_lo_u32 v8, v8, v2
	v_mov_b32_e32 v2, s4
	v_add_co_u32_e32 v2, vcc, 0x3000, v2
	v_mov_b32_e32 v3, s5
	s_nop 0
	v_addc_co_u32_e32 v3, vcc, 0, v3, vcc
	flat_load_dword v2, v[2:3] offset:1024 sc1
	s_add_u32 s10, s4, 0x3400
	s_addc_u32 s11, s5, 0
	s_waitcnt vmcnt(0) lgkmcnt(0)
	v_cmp_lt_u32_e32 vcc, v2, v8
	s_and_saveexec_b64 s[8:9], vcc
	s_cbranch_execz .LBB0_341
	s_mov_b32 s27, 1
	s_mov_b64 s[12:13], 0
	s_branch .LBB0_333

.LBB0_337:
	s_andn2_b64 s[16:17], s[16:17], exec
	s_and_b64 s[22:23], s[22:23], exec
	s_or_b64 s[16:17], s[16:17], s[22:23]
	s_and_saveexec_b64 s[22:23], s[20:21]
	s_cbranch_execz .LBB0_332
	v_mov_b64_e32 v[2:3], s[10:11]
	flat_load_dword v2, v[2:3] sc1
	s_add_i32 s27, s27, 1
	s_or_b64 s[16:17], s[16:17], exec
	s_waitcnt vmcnt(0) lgkmcnt(0)
	v_cmp_ge_u32_e32 vcc, v2, v8
	s_orn2_b64 s[18:19], vcc, exec
	s_branch .LBB0_332

.LBB0_342:
	s_andn2_saveexec_b64 s[6:7], s[6:7]
	s_cbranch_execz .LBB0_358
	v_mov_b32_e32 v1, s4
	v_add_co_u32_e32 v4, vcc, 0x3000, v1
	v_mov_b32_e32 v1, s5
	buffer_wbl2 sc1
	s_waitcnt vmcnt(0)
	v_addc_co_u32_e32 v5, vcc, 0, v1, vcc
	flat_atomic_add v1, v[4:5], v223 offset:1024 sc0
	v_cvt_f32_u32_e32 v3, v2
	v_sub_u32_e32 v4, 0, v2
	s_add_u32 s6, s4, 0x3400
	s_addc_u32 s7, s5, 0
	v_rcp_iflag_f32_e32 v3, v3
	s_mov_b64 s[10:11], 0
	v_mul_f32_e32 v3, 0x4f7ffffe, v3
	v_cvt_u32_f32_e32 v3, v3
	v_mul_lo_u32 v4, v4, v3
	v_mul_hi_u32 v4, v3, v4
	v_add_u32_e32 v3, v3, v4
	s_waitcnt vmcnt(0) lgkmcnt(0)
	v_mul_hi_u32 v3, v1, v3
	v_mul_lo_u32 v5, v3, v2
	v_add_u32_e32 v4, 1, v1
	v_sub_u32_e32 v1, v1, v5
	v_add_u32_e32 v6, 1, v3
	v_cmp_ge_u32_e32 vcc, v1, v2
	v_sub_u32_e32 v5, v1, v2
	s_nop 0
	v_cndmask_b32_e32 v3, v3, v6, vcc
	v_cndmask_b32_e32 v1, v1, v5, vcc
	v_add_u32_e32 v5, 1, v3
	v_cmp_ge_u32_e32 vcc, v1, v2
	s_nop 1
	v_cndmask_b32_e32 v1, v3, v5, vcc
	v_mad_u64_u32 v[2:3], s[8:9], v2, v1, v[2:3]
	v_mov_b32_e32 v8, v2
	v_cmp_ne_u32_e32 vcc, v4, v2
	v_mov_b64_e32 v[2:3], s[6:7]
	s_and_saveexec_b64 s[8:9], vcc
	s_cbranch_execz .LBB0_355
	v_mov_b64_e32 v[2:3], s[6:7]
	flat_load_dword v2, v[2:3] sc1
	s_mov_b64 s[14:15], 0
	s_waitcnt vmcnt(0) lgkmcnt(0)
	v_cmp_lt_u32_e32 vcc, v2, v8
	s_and_saveexec_b64 s[12:13], vcc
	s_cbranch_execz .LBB0_354
	s_add_u32 s10, s4, 0x200
	s_addc_u32 s11, s5, 0
	s_mov_b32 s24, 1
	s_mov_b64 s[4:5], 0
	s_branch .LBB0_347

.LBB0_352:
	v_mov_b64_e32 v[2:3], s[6:7]
	flat_load_dword v2, v[2:3] sc1
	s_add_i32 s24, s24, 1
	s_or_b64 s[18:19], s[18:19], exec
	s_waitcnt vmcnt(0) lgkmcnt(0)
	v_cmp_ge_u32_e32 vcc, v2, v8
	s_orn2_b64 s[16:17], vcc, exec
	s_branch .LBB0_346

.LBB0_357:
	s_or_b64 exec, exec, s[4:5]
	v_mov_b32_e32 v1, s26
	v_add_co_u32_e32 v2, vcc, 0x2000, v1
	v_mov_b32_e32 v1, s3
	s_nop 0
	v_addc_co_u32_e32 v3, vcc, 0, v1, vcc
	s_waitcnt vmcnt(0) lgkmcnt(0)
	buffer_inv sc1
	s_waitcnt vmcnt(0)
